# two-tiles-per-barrier MoBA loop with all waves issuing their DMA pieces right after the barrier (no group de-synchronisation)
# speedup vs baseline: 1.0065x; 1.0065x over previous
.LBB0_1059:
.LBB0_1060:
.LBB0_1062:
.Lmb1_A:
	s_barrier
	s_cmp_eq_u32 s37, 0
	s_cbranch_scc1 .Lmb1_f1A
	s_mov_b32 s45, s37
	s_cmp_ge_u32 s45, s30
	s_cbranch_scc1 .Lmb1_k0A
	s_mov_b32 s45, s44
	s_and_b32 s45, s45, 0x6000
	s_add_i32 s45, s45, s74
	s_mov_b32 s99, m0
	s_mov_b32 m0, s45
	s_nop 0
	global_load_lds_dwordx4 v[114:115], off
	s_mov_b32 m0, s99

; #define ATT_LAS __attribute__((address_space(3)))
; #define ATT_MFMA(a, b, c) __builtin_amdgcn_mfma_f32_32x32x16_bf16((a), (b), (c), 0, 0, 0)
; __device__ __forceinline__ void qkt(f32x16& p0, f32x16& p1, lds_cptr kb, const bf16x8* qr, const f32x16& z) {
; #pragma unroll
;     for (int d0 = 0; d0 < 4; ++d0) {
;         const bf16x8 b0 = *(const ATT_LAS bf16x8*)(kb + d0 * 2048);
;         const bf16x8 b1 = *(const ATT_LAS bf16x8*)(kb + d0 * 2048 + 512);
;         if (d0 == 0) { p0 = ATT_MFMA(b0, qr[0], z); p1 = ATT_MFMA(b1, qr[0], z); }
;         else { p0 = ATT_MFMA(b0, qr[d0], p0); p1 = ATT_MFMA(b1, qr[d0], p1); } }
; }
; __device__ __forceinline__ void pv(f32x16* o, int vb, bf16x8 pa0, bf16x8 pa1, bf16x8 pa2, bf16x8 pa3) {
; #pragma unroll
;     for (int d0 = 0; d0 < 2; ++d0) { s16x4 lo[4], hi[4];
; #pragma unroll
;         for (int ks = 0; ks < 4; ++ks) {
;             asm volatile("ds_read_b64_tr_b16 %0,%1 offset:%c2" : "=&v"(lo[ks]) : "v"(vb), "i"(d0 * 4096 + ks * 1024) : "memory");
;             asm volatile("ds_read_b64_tr_b16 %0,%1 offset:%c2" : "=&v"(hi[ks]) : "v"(vb), "i"(d0 * 4096 + ks * 1024 + 512) : "memory"); }
;         asm volatile("s_waitcnt lgkmcnt(0)" ::: "memory"); __builtin_amdgcn_sched_barrier(0);
;     ...
;         o[d0] = ATT_MFMA(pa0, ATT_PK(0), o[d0]);
;         o[d0] = ATT_MFMA(pa1, ATT_PK(1), o[d0]);
;         o[d0] = ATT_MFMA(pa2, ATT_PK(2), o[d0]);
;         o[d0] = ATT_MFMA(pa3, ATT_PK(3), o[d0]);
;     ...
;     }
; }
.Lmb1_v1A:
	v_lshl_add_u64 v[116:117], v[116:117], 0, s[22:23]
	s_add_i32 s42, s44, 0x2000
	s_add_i32 s98, s44, 0x4000
	s_and_b32 s45, s98, 0x6000
	v_add_u32_e32 v133, s45, v130
	ds_read_b128 v[154:157], v133
	ds_read_b128 v[158:161], v133 offset:512
	ds_read_b128 v[162:165], v133 offset:2048
	ds_read_b128 v[166:169], v133 offset:2560
	ds_read_b128 v[170:173], v133 offset:4096
	ds_read_b128 v[174:177], v133 offset:4608
	ds_read_b128 v[178:181], v133 offset:6144
	ds_read_b128 v[182:185], v133 offset:6656
	s_and_b32 s45, s42, 0x6000
	v_add_u32_e32 v218, s45, v132
	s_add_i32 s98, s34, 2
	s_cmp_ge_i32 s34, s31
	s_cbranch_scc1 .Lmb1_A_near
	v_mfma_f32_32x32x16_bf16 v[16:31], v[108:111], v[186:189], v[16:31]
	v_exp_f32_e32 v64, v64
	v_exp_f32_e32 v48, v48
	v_mfma_f32_32x32x16_bf16 v[16:31], v[104:107], v[190:193], v[16:31]
	v_exp_f32_e32 v65, v65
	v_exp_f32_e32 v49, v49
	v_add_f32_e32 v252, v64, v48
	v_mfma_f32_32x32x16_bf16 v[16:31], v[100:103], v[194:197], v[16:31]
	v_exp_f32_e32 v66, v66
	v_exp_f32_e32 v50, v50
	v_add_f32_e32 v253, v65, v49
	v_add_f32_e32 v252, v252, v253
	v_mfma_f32_32x32x16_bf16 v[16:31], v[96:99], v[198:201], v[16:31]
	v_exp_f32_e32 v67, v67
	v_exp_f32_e32 v51, v51
	v_add_f32_e32 v253, v66, v50
	v_add_f32_e32 v252, v252, v253
	v_mfma_f32_32x32x16_bf16 v[32:47], v[108:111], v[202:205], v[32:47]
	v_exp_f32_e32 v68, v68
	v_exp_f32_e32 v52, v52
	v_add_f32_e32 v253, v67, v51
	v_add_f32_e32 v252, v252, v253
	ds_read_b64_tr_b16 v[186:187], v218
	ds_read_b64_tr_b16 v[188:189], v218 offset:512
	v_mfma_f32_32x32x16_bf16 v[32:47], v[104:107], v[206:209], v[32:47]
	v_exp_f32_e32 v69, v69
	v_exp_f32_e32 v53, v53
	v_add_f32_e32 v253, v68, v52
	v_add_f32_e32 v252, v252, v253
	ds_read_b64_tr_b16 v[190:191], v218 offset:1024
	ds_read_b64_tr_b16 v[192:193], v218 offset:1536
	v_mfma_f32_32x32x16_bf16 v[32:47], v[100:103], v[210:213], v[32:47]
	v_exp_f32_e32 v70, v70
	v_exp_f32_e32 v54, v54
	v_add_f32_e32 v253, v69, v53
	v_add_f32_e32 v252, v252, v253
	ds_read_b64_tr_b16 v[194:195], v218 offset:2048
	ds_read_b64_tr_b16 v[196:197], v218 offset:2560
	v_mfma_f32_32x32x16_bf16 v[32:47], v[96:99], v[214:217], v[32:47]
	v_exp_f32_e32 v71, v71
	v_exp_f32_e32 v55, v55
	v_add_f32_e32 v253, v70, v54
	v_add_f32_e32 v252, v252, v253
	ds_read_b64_tr_b16 v[198:199], v218 offset:3072
	ds_read_b64_tr_b16 v[200:201], v218 offset:3584
	s_waitcnt lgkmcnt(8)
	v_mfma_f32_32x32x16_bf16 v[236:251], v[154:157], v[92:95], v[220:235]
	v_exp_f32_e32 v72, v72
	v_exp_f32_e32 v56, v56
	v_add_f32_e32 v253, v71, v55
	v_add_f32_e32 v252, v252, v253
	v_cvt_pk_bf16_f32 v108, v64, v65
	v_cvt_pk_bf16_f32 v100, v48, v49
	ds_read_b64_tr_b16 v[202:203], v218 offset:4096
	ds_read_b64_tr_b16 v[204:205], v218 offset:4608
	v_mfma_f32_32x32x16_bf16 v[134:149], v[158:161], v[92:95], v[220:235]
	v_exp_f32_e32 v73, v73
	v_exp_f32_e32 v57, v57
	v_add_f32_e32 v253, v72, v56
	v_add_f32_e32 v252, v252, v253
	v_cvt_pk_bf16_f32 v109, v66, v67
	v_cvt_pk_bf16_f32 v101, v50, v51
	ds_read_b64_tr_b16 v[206:207], v218 offset:5120
	ds_read_b64_tr_b16 v[208:209], v218 offset:5632
	v_mfma_f32_32x32x16_bf16 v[236:251], v[162:165], v[88:91], v[236:251]
	v_exp_f32_e32 v74, v74
	v_exp_f32_e32 v58, v58
	v_add_f32_e32 v253, v73, v57
	v_add_f32_e32 v252, v252, v253
	v_cvt_pk_bf16_f32 v110, v68, v69
	v_cvt_pk_bf16_f32 v102, v52, v53
	ds_read_b64_tr_b16 v[210:211], v218 offset:6144
	ds_read_b64_tr_b16 v[212:213], v218 offset:6656
	v_mfma_f32_32x32x16_bf16 v[134:149], v[166:169], v[88:91], v[134:149]
	v_exp_f32_e32 v75, v75
	v_exp_f32_e32 v59, v59
	v_add_f32_e32 v253, v74, v58
	v_add_f32_e32 v252, v252, v253
	v_cvt_pk_bf16_f32 v111, v70, v71
	v_cvt_pk_bf16_f32 v103, v54, v55
	ds_read_b64_tr_b16 v[214:215], v218 offset:7168
	ds_read_b64_tr_b16 v[216:217], v218 offset:7680
	v_mfma_f32_32x32x16_bf16 v[236:251], v[170:173], v[84:87], v[236:251]
	v_exp_f32_e32 v76, v76
	v_exp_f32_e32 v60, v60
	v_add_f32_e32 v253, v75, v59
	v_add_f32_e32 v252, v252, v253
	v_cvt_pk_bf16_f32 v104, v72, v73
	v_cvt_pk_bf16_f32 v96, v56, v57
	v_mfma_f32_32x32x16_bf16 v[134:149], v[174:177], v[84:87], v[134:149]
	v_exp_f32_e32 v77, v77
	v_exp_f32_e32 v61, v61
	v_add_f32_e32 v253, v76, v60
	v_add_f32_e32 v252, v252, v253
	v_cvt_pk_bf16_f32 v105, v74, v75
	v_cvt_pk_bf16_f32 v97, v58, v59
	v_mfma_f32_32x32x16_bf16 v[236:251], v[178:181], v[80:83], v[236:251]
	v_exp_f32_e32 v78, v78
	v_exp_f32_e32 v62, v62
	v_add_f32_e32 v253, v77, v61
	v_add_f32_e32 v252, v252, v253
	v_cvt_pk_bf16_f32 v106, v76, v77
	v_cvt_pk_bf16_f32 v98, v60, v61
	v_mfma_f32_32x32x16_bf16 v[134:149], v[182:185], v[80:83], v[134:149]
	v_exp_f32_e32 v79, v79
	v_exp_f32_e32 v63, v63
	v_add_f32_e32 v253, v78, v62
	v_add_f32_e32 v252, v252, v253
	v_add_f32_e32 v253, v79, v63
	v_add_f32_e32 v252, v252, v253
	v_cvt_pk_bf16_f32 v107, v78, v79
	v_cvt_pk_bf16_f32 v99, v62, v63
	v_add_f32_e32 v131, v131, v252

.LBB0_2383:
.LBB0_2384:
.LBB0_2386:
.Lmb3_A:
	s_barrier
	s_cmp_eq_u32 s35, 0
	s_cbranch_scc1 .Lmb3_f1A
	s_mov_b32 s42, s35
	s_cmp_ge_u32 s42, s28
	s_cbranch_scc1 .Lmb3_k0A
	s_mov_b32 s42, s43
	s_and_b32 s42, s42, 0x6000
	s_add_i32 s42, s42, s74
	s_mov_b32 s99, m0
	s_mov_b32 m0, s42
	s_nop 0
	global_load_lds_dwordx4 v[114:115], off
	s_mov_b32 m0, s99

; #define ATT_LAS __attribute__((address_space(3)))
; #define ATT_MFMA(a, b, c) __builtin_amdgcn_mfma_f32_32x32x16_bf16((a), (b), (c), 0, 0, 0)
; __device__ __forceinline__ void qkt(f32x16& p0, f32x16& p1, lds_cptr kb, const bf16x8* qr, const f32x16& z) {
; #pragma unroll
;     for (int d0 = 0; d0 < 4; ++d0) {
;         const bf16x8 b0 = *(const ATT_LAS bf16x8*)(kb + d0 * 2048);
;         const bf16x8 b1 = *(const ATT_LAS bf16x8*)(kb + d0 * 2048 + 512);
;         if (d0 == 0) { p0 = ATT_MFMA(b0, qr[0], z); p1 = ATT_MFMA(b1, qr[0], z); }
;         else { p0 = ATT_MFMA(b0, qr[d0], p0); p1 = ATT_MFMA(b1, qr[d0], p1); } }
; }
; __device__ __forceinline__ void pv(f32x16* o, int vb, bf16x8 pa0, bf16x8 pa1, bf16x8 pa2, bf16x8 pa3) {
; #pragma unroll
;     for (int d0 = 0; d0 < 2; ++d0) { s16x4 lo[4], hi[4];
; #pragma unroll
;         for (int ks = 0; ks < 4; ++ks) {
;             asm volatile("ds_read_b64_tr_b16 %0,%1 offset:%c2" : "=&v"(lo[ks]) : "v"(vb), "i"(d0 * 4096 + ks * 1024) : "memory");
;             asm volatile("ds_read_b64_tr_b16 %0,%1 offset:%c2" : "=&v"(hi[ks]) : "v"(vb), "i"(d0 * 4096 + ks * 1024 + 512) : "memory"); }
;         asm volatile("s_waitcnt lgkmcnt(0)" ::: "memory"); __builtin_amdgcn_sched_barrier(0);
;     ...
;         o[d0] = ATT_MFMA(pa0, ATT_PK(0), o[d0]);
;         o[d0] = ATT_MFMA(pa1, ATT_PK(1), o[d0]);
;         o[d0] = ATT_MFMA(pa2, ATT_PK(2), o[d0]);
;         o[d0] = ATT_MFMA(pa3, ATT_PK(3), o[d0]);
;     ...
;     }
; }
.Lmb3_v1A:
	v_lshl_add_u64 v[116:117], v[116:117], 0, s[20:21]
	s_add_i32 s36, s43, 0x2000
	s_add_i32 s98, s43, 0x4000
	s_and_b32 s42, s98, 0x6000
	v_add_u32_e32 v133, s42, v130
	ds_read_b128 v[154:157], v133
	ds_read_b128 v[158:161], v133 offset:512
	ds_read_b128 v[162:165], v133 offset:2048
	ds_read_b128 v[166:169], v133 offset:2560
	ds_read_b128 v[170:173], v133 offset:4096
	ds_read_b128 v[174:177], v133 offset:4608
	ds_read_b128 v[178:181], v133 offset:6144
	ds_read_b128 v[182:185], v133 offset:6656
	s_and_b32 s42, s36, 0x6000
	v_add_u32_e32 v218, s42, v132
	s_add_i32 s98, s30, 2
	s_cmp_ge_i32 s30, s29
	s_cbranch_scc1 .Lmb3_A_near
	v_mfma_f32_32x32x16_bf16 v[16:31], v[108:111], v[186:189], v[16:31]
	v_exp_f32_e32 v64, v64
	v_exp_f32_e32 v48, v48
	v_mfma_f32_32x32x16_bf16 v[16:31], v[104:107], v[190:193], v[16:31]
	v_exp_f32_e32 v65, v65
	v_exp_f32_e32 v49, v49
	v_add_f32_e32 v252, v64, v48
	v_mfma_f32_32x32x16_bf16 v[16:31], v[100:103], v[194:197], v[16:31]
	v_exp_f32_e32 v66, v66
	v_exp_f32_e32 v50, v50
	v_add_f32_e32 v253, v65, v49
	v_add_f32_e32 v252, v252, v253
	v_mfma_f32_32x32x16_bf16 v[16:31], v[96:99], v[198:201], v[16:31]
	v_exp_f32_e32 v67, v67
	v_exp_f32_e32 v51, v51
	v_add_f32_e32 v253, v66, v50
	v_add_f32_e32 v252, v252, v253
	v_mfma_f32_32x32x16_bf16 v[32:47], v[108:111], v[202:205], v[32:47]
	v_exp_f32_e32 v68, v68
	v_exp_f32_e32 v52, v52
	v_add_f32_e32 v253, v67, v51
	v_add_f32_e32 v252, v252, v253
	ds_read_b64_tr_b16 v[186:187], v218
	ds_read_b64_tr_b16 v[188:189], v218 offset:512
	v_mfma_f32_32x32x16_bf16 v[32:47], v[104:107], v[206:209], v[32:47]
	v_exp_f32_e32 v69, v69
	v_exp_f32_e32 v53, v53
	v_add_f32_e32 v253, v68, v52
	v_add_f32_e32 v252, v252, v253
	ds_read_b64_tr_b16 v[190:191], v218 offset:1024
	ds_read_b64_tr_b16 v[192:193], v218 offset:1536
	v_mfma_f32_32x32x16_bf16 v[32:47], v[100:103], v[210:213], v[32:47]
	v_exp_f32_e32 v70, v70
	v_exp_f32_e32 v54, v54
	v_add_f32_e32 v253, v69, v53
	v_add_f32_e32 v252, v252, v253
	ds_read_b64_tr_b16 v[194:195], v218 offset:2048
	ds_read_b64_tr_b16 v[196:197], v218 offset:2560
	v_mfma_f32_32x32x16_bf16 v[32:47], v[96:99], v[214:217], v[32:47]
	v_exp_f32_e32 v71, v71
	v_exp_f32_e32 v55, v55
	v_add_f32_e32 v253, v70, v54
	v_add_f32_e32 v252, v252, v253
	ds_read_b64_tr_b16 v[198:199], v218 offset:3072
	ds_read_b64_tr_b16 v[200:201], v218 offset:3584
	s_waitcnt lgkmcnt(8)
	v_mfma_f32_32x32x16_bf16 v[236:251], v[154:157], v[92:95], v[220:235]
	v_exp_f32_e32 v72, v72
	v_exp_f32_e32 v56, v56
	v_add_f32_e32 v253, v71, v55
	v_add_f32_e32 v252, v252, v253
	v_cvt_pk_bf16_f32 v108, v64, v65
	v_cvt_pk_bf16_f32 v100, v48, v49
	ds_read_b64_tr_b16 v[202:203], v218 offset:4096
	ds_read_b64_tr_b16 v[204:205], v218 offset:4608
	v_mfma_f32_32x32x16_bf16 v[134:149], v[158:161], v[92:95], v[220:235]
	v_exp_f32_e32 v73, v73
	v_exp_f32_e32 v57, v57
	v_add_f32_e32 v253, v72, v56
	v_add_f32_e32 v252, v252, v253
	v_cvt_pk_bf16_f32 v109, v66, v67
	v_cvt_pk_bf16_f32 v101, v50, v51
	ds_read_b64_tr_b16 v[206:207], v218 offset:5120
	ds_read_b64_tr_b16 v[208:209], v218 offset:5632
	v_mfma_f32_32x32x16_bf16 v[236:251], v[162:165], v[88:91], v[236:251]
	v_exp_f32_e32 v74, v74
	v_exp_f32_e32 v58, v58
	v_add_f32_e32 v253, v73, v57
	v_add_f32_e32 v252, v252, v253
	v_cvt_pk_bf16_f32 v110, v68, v69
	v_cvt_pk_bf16_f32 v102, v52, v53
	ds_read_b64_tr_b16 v[210:211], v218 offset:6144
	ds_read_b64_tr_b16 v[212:213], v218 offset:6656
	v_mfma_f32_32x32x16_bf16 v[134:149], v[166:169], v[88:91], v[134:149]
	v_exp_f32_e32 v75, v75
	v_exp_f32_e32 v59, v59
	v_add_f32_e32 v253, v74, v58
	v_add_f32_e32 v252, v252, v253
	v_cvt_pk_bf16_f32 v111, v70, v71
	v_cvt_pk_bf16_f32 v103, v54, v55
	ds_read_b64_tr_b16 v[214:215], v218 offset:7168
	ds_read_b64_tr_b16 v[216:217], v218 offset:7680
	v_mfma_f32_32x32x16_bf16 v[236:251], v[170:173], v[84:87], v[236:251]
	v_exp_f32_e32 v76, v76
	v_exp_f32_e32 v60, v60
	v_add_f32_e32 v253, v75, v59
	v_add_f32_e32 v252, v252, v253
	v_cvt_pk_bf16_f32 v104, v72, v73
	v_cvt_pk_bf16_f32 v96, v56, v57
	v_mfma_f32_32x32x16_bf16 v[134:149], v[174:177], v[84:87], v[134:149]
	v_exp_f32_e32 v77, v77
	v_exp_f32_e32 v61, v61
	v_add_f32_e32 v253, v76, v60
	v_add_f32_e32 v252, v252, v253
	v_cvt_pk_bf16_f32 v105, v74, v75
	v_cvt_pk_bf16_f32 v97, v58, v59
	v_mfma_f32_32x32x16_bf16 v[236:251], v[178:181], v[80:83], v[236:251]
	v_exp_f32_e32 v78, v78
	v_exp_f32_e32 v62, v62
	v_add_f32_e32 v253, v77, v61
	v_add_f32_e32 v252, v252, v253
	v_cvt_pk_bf16_f32 v106, v76, v77
	v_cvt_pk_bf16_f32 v98, v60, v61
	v_mfma_f32_32x32x16_bf16 v[134:149], v[182:185], v[80:83], v[134:149]
	v_exp_f32_e32 v79, v79
	v_exp_f32_e32 v63, v63
	v_add_f32_e32 v253, v78, v62
	v_add_f32_e32 v252, v252, v253
	v_add_f32_e32 v253, v79, v63
	v_add_f32_e32 v252, v252, v253
	v_cvt_pk_bf16_f32 v107, v78, v79
	v_cvt_pk_bf16_f32 v99, v62, v63
	v_add_f32_e32 v131, v131, v252
